# stack + merge epilogue: first 8 third-gate loads issued before the merge K-loop (v192-207), first epilogue wait removed
# speedup vs baseline: 1.0126x; 1.0046x over previous
; template <class Epi, class Order = StaticOrder, bool HALFN = false>
; __device__ __forceinline__ void gemm_phase(LAS unsigned char* lds, const Gemm g, const Epi& E) {
;     ...
;         else {
; #pragma unroll
;         for (int a = 0; a < 2; ++a)
; #pragma unroll
;             for (int b = 0; b < 2; ++b)
; #pragma unroll
;                 for (int m = 0; m < 4; ++m)
; #pragma unroll
;                     for (int n = 0; n < 2; ++n) acc[a][b][m][n] = (f32x4){0.f, 0.f, 0.f, 0.f};
;         }
;         cur = nxt; cA = nA; cB = nB; ++ui;
;     __device__ __forceinline__ void operator()(f32x4 (&acc)[2][2][4][2], const Unit& u, int wr, int wc, int fr, int fq) const {
;     ...
;                 for (int bj = 0; bj < 2; ++bj) { const int row = u.pm * 256 + ai * 128 + wr * 64 + m * 16 + fr, col = u.pn * 256 + bj * 128 + wc * 32 + 8 * fq;
;                     gg[m][bj] = *(const u32x2*)((const unsigned char*)P + (size_t)row * ROWB + GATE_B0 + 2 * DM + col); }
.LBB0_613:
	s_lshl_b32 s8, s27, 8
	s_lshl_b32 s4, s26, 8
	s_or_b32 s42, s4, s21
	s_or_b32 s43, s8, 0x80
	s_add_u32 s4, s52, 0xc0080
	s_addc_u32 s5, s53, 0
	v_mov_b32_e32 v2, v0
	v_mov_b32_e32 v3, v0
	s_add_u32 s62, s54, 0x100
	v_mov_b32_e32 v1, v0
	v_mov_b64_e32 v[6:7], v[2:3]
	v_mov_b64_e32 v[10:11], v[2:3]
	v_mov_b64_e32 v[22:23], v[2:3]
	v_mov_b64_e32 v[26:27], v[2:3]
	v_mov_b64_e32 v[38:39], v[2:3]
	v_mov_b64_e32 v[42:43], v[2:3]
	v_mov_b64_e32 v[54:55], v[2:3]
	v_mov_b64_e32 v[58:59], v[2:3]
	v_mov_b64_e32 v[14:15], v[2:3]
	v_mov_b64_e32 v[18:19], v[2:3]
	v_mov_b64_e32 v[30:31], v[2:3]
	v_mov_b64_e32 v[34:35], v[2:3]
	v_mov_b64_e32 v[46:47], v[2:3]
	v_mov_b64_e32 v[50:51], v[2:3]
	v_mov_b64_e32 v[62:63], v[2:3]
	v_mov_b64_e32 v[66:67], v[2:3]
	v_mov_b64_e32 v[70:71], v[2:3]
	v_mov_b64_e32 v[74:75], v[2:3]
	v_mov_b64_e32 v[86:87], v[2:3]
	v_mov_b64_e32 v[90:91], v[2:3]
	v_mov_b64_e32 v[102:103], v[2:3]
	v_mov_b64_e32 v[106:107], v[2:3]
	v_mov_b64_e32 v[118:119], v[2:3]
	v_mov_b64_e32 v[122:123], v[2:3]
	v_mov_b64_e32 v[78:79], v[2:3]
	v_mov_b64_e32 v[82:83], v[2:3]
	v_mov_b64_e32 v[94:95], v[2:3]
	v_mov_b64_e32 v[98:99], v[2:3]
	v_mov_b64_e32 v[110:111], v[2:3]
	v_mov_b64_e32 v[114:115], v[2:3]
	v_mov_b64_e32 v[126:127], v[2:3]
	v_mov_b64_e32 v[130:131], v[2:3]
	v_lshl_add_u64 v[144:145], s[4:5], 0, v[140:141]
	v_lshl_add_u64 v[146:147], s[4:5], 0, v[142:143]
	s_addc_u32 s63, s55, 0
	s_mov_b32 s74, 0
	s_mov_b64 s[54:55], 0
	v_mov_b64_e32 v[4:5], v[0:1]
	v_mov_b64_e32 v[8:9], v[0:1]
	v_mov_b64_e32 v[20:21], v[0:1]
	v_mov_b64_e32 v[24:25], v[0:1]
	v_mov_b64_e32 v[36:37], v[0:1]
	v_mov_b64_e32 v[40:41], v[0:1]
	v_mov_b64_e32 v[52:53], v[0:1]
	v_mov_b64_e32 v[56:57], v[0:1]
	v_mov_b64_e32 v[12:13], v[0:1]
	v_mov_b64_e32 v[16:17], v[0:1]
	v_mov_b64_e32 v[28:29], v[0:1]
	v_mov_b64_e32 v[32:33], v[0:1]
	v_mov_b64_e32 v[44:45], v[0:1]
	v_mov_b64_e32 v[48:49], v[0:1]
	v_mov_b64_e32 v[60:61], v[0:1]
	v_mov_b64_e32 v[64:65], v[0:1]
	v_mov_b64_e32 v[68:69], v[0:1]
	v_mov_b64_e32 v[72:73], v[0:1]
	v_mov_b64_e32 v[84:85], v[0:1]
	v_mov_b64_e32 v[88:89], v[0:1]
	v_mov_b64_e32 v[100:101], v[0:1]
	v_mov_b64_e32 v[104:105], v[0:1]
	v_mov_b64_e32 v[116:117], v[0:1]
	v_mov_b64_e32 v[120:121], v[0:1]
	v_mov_b64_e32 v[76:77], v[0:1]
	v_mov_b64_e32 v[80:81], v[0:1]
	v_mov_b64_e32 v[92:93], v[0:1]
	v_mov_b64_e32 v[96:97], v[0:1]
	v_mov_b64_e32 v[108:109], v[0:1]
	v_mov_b64_e32 v[112:113], v[0:1]
	v_mov_b64_e32 v[124:125], v[0:1]
	v_mov_b64_e32 v[128:129], v[0:1]
	s_lshr_b32 s98, s42, 7
	s_bfe_u32 s99, s42, 0x10006
	s_or_b32 s98, s98, s99
	v_sub_u32_e32 v255, s98, v180
	s_and_b32 s99, s42, 32
	s_lshl_b32 s99, s99, 4
	s_addk_i32 s99, 0x4000
	v_lshl_add_u32 v204, v181, 7, s99
	v_lshl_add_u32 v204, v180, 3, v204
	v_mad_i32_i24 v204, v255, s33, v204
	v_ashrrev_i32_e32 v205, 31, v204
	v_lshl_add_u64 v[204:205], s[68:69], 0, v[204:205]
	s_add_i32 s98, s8, s20
	v_add_u32_e32 v254, s98, v180
	v_mad_i64_i32 v[206:207], s[98:99], v254, s33, v[204:205]
	global_load_dwordx2 v[192:193], v[206:207], off
	global_load_dwordx2 v[194:195], v[206:207], off offset:1024
	v_add_u32_e32 v254, 16, v254
	v_mad_i64_i32 v[206:207], s[98:99], v254, s33, v[204:205]
	global_load_dwordx2 v[196:197], v[206:207], off
	global_load_dwordx2 v[198:199], v[206:207], off offset:1024
	v_add_u32_e32 v254, 16, v254
	v_mad_i64_i32 v[206:207], s[98:99], v254, s33, v[204:205]
	global_load_dwordx2 v[200:201], v[206:207], off
	global_load_dwordx2 v[202:203], v[206:207], off offset:1024
	v_add_u32_e32 v254, 16, v254
	v_mad_i64_i32 v[206:207], s[98:99], v254, s33, v[204:205]
	global_load_dwordx2 v[204:205], v[206:207], off
	global_load_dwordx2 v[206:207], v[206:207], off offset:1024
	s_cmp_lt_i32 s74, 32
	s_cbranch_scc1 .LBB0_615

; __device__ __forceinline__ u32x4 pack8(f32x4 a, f32x4 b) { u32x4 w; w.x = cvt_pk_bf16(a[0], a[1]); w.y = cvt_pk_bf16(a[2], a[3]); w.z = cvt_pk_bf16(b[0], b[1]); w.w = cvt_pk_bf16(b[2], b[3]); return w; }
; __device__ __forceinline__ f32x4 un_unorm8(unsigned w) { return (f32x4){fmaxf((float)(w & 255u), 0.5f), fmaxf((float)((w >> 8) & 255u), 0.5f), fmaxf((float)((w >> 16) & 255u), 0.5f), fmaxf((float)(w >> 24), 0.5f)}; }
;     __device__ __forceinline__ void operator()(f32x4 (&acc)[2][2][4][2], const Unit& u, int wr, int wc, int fr, int fq) const {
;     ...
;         for (int ai = 0; ai < 2; ++ai) {
;             u32x2 gg[4][2];
; #pragma unroll
;             for (int m = 0; m < 4; ++m)
; #pragma unroll
;                 for (int bj = 0; bj < 2; ++bj) { const int row = u.pm * 256 + ai * 128 + wr * 64 + m * 16 + fr, col = u.pn * 256 + bj * 128 + wc * 32 + 8 * fq;
;                     gg[m][bj] = *(const u32x2*)((const unsigned char*)P + (size_t)row * ROWB + GATE_B0 + 2 * DM + col); }
;             asm volatile("" ::: "memory");
; #pragma unroll
;             for (int m = 0; m < 4; ++m)
; #pragma unroll
;                 for (int bj = 0; bj < 2; ++bj) { const int row = u.pm * 256 + ai * 128 + wr * 64 + m * 16 + fr, col = u.pn * 256 + bj * 128 + wc * 32 + 8 * fq;
;                     const f32x4 g0 = un_unorm8(gg[m][bj].x) * (1.0f / 255.0f), g1 = un_unorm8(gg[m][bj].y) * (1.0f / 255.0f);
;                     *(u32x4*)(MG + (size_t)row * DM + col) = pack8(acc[ai][bj][m][0] * g0, acc[ai][bj][m][1] * g1); }
.LBB0_623:
	v_mov_b32_e32 v1, v181
	v_mov_b32_e32 v2, v180
	s_add_i32 s8, s8, s20
	v_mov_b64_e32 v[150:151], s[68:69]
	s_lshr_b32 s98, s42, 7
	s_bfe_u32 s99, s42, 0x10006
	s_or_b32 s98, s98, s99
	v_sub_u32_e32 v245, s98, v180
	s_and_b32 s99, s42, 32
	s_lshl_b32 s99, s99, 4
	v_lshl_add_u32 v246, v181, 7, s99
	v_lshl_add_u32 v246, v180, 3, v246
	v_mad_i32_i24 v246, v245, s33, v246
	v_ashrrev_i32_e32 v247, 31, v246
	v_add_u32_e32 v146, s8, v2
	v_lshl_add_u32 v144, v1, 3, s42
	v_mad_i64_i32 v[2:3], s[4:5], v146, s33, v[150:151]
	v_ashrrev_i32_e32 v145, 31, v144
	v_lshl_add_u64 v[2:3], v[2:3], 0, s[84:85]
	v_lshl_add_u64 v[148:149], v[2:3], 0, v[246:247]
	v_add_u32_e32 v148, 0x400, v246
	v_ashrrev_i32_e32 v149, 31, v148
	v_lshl_add_u64 v[2:3], v[2:3], 0, v[148:149]
	v_add_u32_e32 v174, 16, v146
	v_mad_i64_i32 v[2:3], s[4:5], v174, s33, v[150:151]
	v_lshl_add_u64 v[2:3], v[2:3], 0, s[84:85]
	v_lshl_add_u64 v[152:153], v[2:3], 0, v[246:247]
	v_lshl_add_u64 v[2:3], v[2:3], 0, v[148:149]
	v_add_u32_e32 v170, 32, v146
	v_mad_i64_i32 v[2:3], s[4:5], v170, s33, v[150:151]
	v_lshl_add_u64 v[2:3], v[2:3], 0, s[84:85]
	v_lshl_add_u64 v[152:153], v[2:3], 0, v[246:247]
	v_lshl_add_u64 v[2:3], v[2:3], 0, v[148:149]
	v_add_u32_e32 v156, 48, v146
	v_mad_i64_i32 v[2:3], s[4:5], v156, s33, v[150:151]
	v_lshl_add_u64 v[2:3], v[2:3], 0, s[84:85]
	v_lshl_add_u64 v[152:153], v[2:3], 0, v[246:247]
	v_lshl_add_u64 v[2:3], v[2:3], 0, v[148:149]
	v_ashrrev_i32_e32 v147, 31, v146
	v_lshlrev_b64 v[2:3], 12, v[146:147]
	v_ashrrev_i32_e32 v175, 31, v174
	v_ashrrev_i32_e32 v171, 31, v170
	v_ashrrev_i32_e32 v157, 31, v156
	s_and_b64 vcc, exec, s[40:41]
	v_cvt_f32_ubyte0_e32 v1, v192
	v_max_f32_e32 v184, 0.5, v1
	v_cvt_f32_ubyte1_e32 v1, v192
	v_max_f32_e32 v185, 0.5, v1
	v_cvt_f32_ubyte2_e32 v1, v192
	v_max_f32_e32 v186, 0.5, v1
	v_cvt_f32_ubyte3_e32 v1, v192
	v_max_f32_e32 v187, 0.5, v1
	v_cvt_f32_ubyte0_e32 v1, v193
	v_max_f32_e32 v208, 0.5, v1
	v_cvt_f32_ubyte1_e32 v1, v193
	v_max_f32_e32 v209, 0.5, v1
	v_cvt_f32_ubyte2_e32 v1, v193
	v_max_f32_e32 v178, 0.5, v1
	v_cvt_f32_ubyte3_e32 v1, v193
	v_pk_mul_f32 v[184:185], v[184:185], s[86:87] op_sel_hi:[1,0]
	v_max_f32_e32 v179, 0.5, v1
	v_pk_mul_f32 v[186:187], v[186:187], s[86:87] op_sel_hi:[1,0]
	v_pk_mul_f32 v[208:209], v[208:209], s[86:87] op_sel_hi:[1,0]
	v_pk_mul_f32 v[178:179], v[178:179], s[86:87] op_sel_hi:[1,0]
	v_pk_mul_f32 v[128:129], v[128:129], v[184:185]
	v_pk_mul_f32 v[130:131], v[130:131], v[186:187]
	v_pk_mul_f32 v[178:179], v[126:127], v[178:179]
	v_pk_mul_f32 v[126:127], v[124:125], v[208:209]
	v_cvt_pk_bf16_f32 v124, v128, v129
	v_lshl_add_u64 v[128:129], s[72:73], 0, v[2:3]
	v_lshlrev_b64 v[2:3], 1, v[144:145]
	v_cvt_pk_bf16_f32 v125, v130, v131
	v_cvt_pk_bf16_f32 v126, v126, v127
	v_cvt_pk_bf16_f32 v127, v178, v179
	v_lshl_add_u64 v[128:129], v[128:129], 0, v[2:3]
	v_cvt_f32_ubyte0_e32 v1, v194
	global_store_dwordx4 v[128:129], v[124:127], off
	s_nop 1
	v_max_f32_e32 v124, 0.5, v1
	v_cvt_f32_ubyte1_e32 v1, v194
	v_max_f32_e32 v125, 0.5, v1
	v_cvt_f32_ubyte2_e32 v1, v194
	v_max_f32_e32 v126, 0.5, v1
	v_cvt_f32_ubyte3_e32 v1, v194
	v_max_f32_e32 v127, 0.5, v1
	v_cvt_f32_ubyte0_e32 v1, v195
	v_max_f32_e32 v130, 0.5, v1
	v_cvt_f32_ubyte1_e32 v1, v195
	v_max_f32_e32 v131, 0.5, v1
	v_cvt_f32_ubyte2_e32 v1, v195
	v_max_f32_e32 v176, 0.5, v1
	v_cvt_f32_ubyte3_e32 v1, v195
	v_max_f32_e32 v177, 0.5, v1
	v_pk_mul_f32 v[124:125], v[124:125], s[86:87] op_sel_hi:[1,0]
	v_pk_mul_f32 v[126:127], v[126:127], s[86:87] op_sel_hi:[1,0]
	v_pk_mul_f32 v[130:131], v[130:131], s[86:87] op_sel_hi:[1,0]
	v_pk_mul_f32 v[176:177], v[176:177], s[86:87] op_sel_hi:[1,0]
	v_pk_mul_f32 v[122:123], v[122:123], v[126:127]
	v_pk_mul_f32 v[120:121], v[120:121], v[124:125]
	v_pk_mul_f32 v[124:125], v[118:119], v[176:177]
	v_pk_mul_f32 v[118:119], v[116:117], v[130:131]
	v_cvt_pk_bf16_f32 v116, v120, v121
	v_cvt_pk_bf16_f32 v117, v122, v123
	v_cvt_pk_bf16_f32 v118, v118, v119
	v_cvt_pk_bf16_f32 v119, v124, v125
	v_cvt_f32_ubyte0_e32 v1, v196
	global_store_dwordx4 v[128:129], v[116:119], off offset:256
	s_nop 1
	v_max_f32_e32 v118, 0.5, v1
	v_cvt_f32_ubyte1_e32 v1, v196
	v_max_f32_e32 v119, 0.5, v1
	v_cvt_f32_ubyte2_e32 v1, v196
	v_max_f32_e32 v120, 0.5, v1
	v_cvt_f32_ubyte3_e32 v1, v196
	v_max_f32_e32 v121, 0.5, v1
	v_cvt_f32_ubyte0_e32 v1, v197
	v_max_f32_e32 v122, 0.5, v1
	v_cvt_f32_ubyte1_e32 v1, v197
	v_max_f32_e32 v123, 0.5, v1
	v_cvt_f32_ubyte2_e32 v1, v197
	v_max_f32_e32 v124, 0.5, v1
	v_cvt_f32_ubyte3_e32 v1, v197
	v_pk_mul_f32 v[118:119], v[118:119], s[86:87] op_sel_hi:[1,0]
	v_max_f32_e32 v125, 0.5, v1
	v_lshlrev_b64 v[116:117], 12, v[174:175]
	v_pk_mul_f32 v[120:121], v[120:121], s[86:87] op_sel_hi:[1,0]
	v_pk_mul_f32 v[122:123], v[122:123], s[86:87] op_sel_hi:[1,0]
	v_pk_mul_f32 v[124:125], v[124:125], s[86:87] op_sel_hi:[1,0]
	v_pk_mul_f32 v[112:113], v[112:113], v[118:119]
	v_pk_mul_f32 v[114:115], v[114:115], v[120:121]
	v_pk_mul_f32 v[118:119], v[110:111], v[124:125]
	v_pk_mul_f32 v[110:111], v[108:109], v[122:123]
	v_cvt_pk_bf16_f32 v108, v112, v113
	v_lshl_add_u64 v[112:113], s[72:73], 0, v[116:117]
	v_cvt_pk_bf16_f32 v109, v114, v115
	v_cvt_pk_bf16_f32 v110, v110, v111
	v_cvt_pk_bf16_f32 v111, v118, v119
	v_lshl_add_u64 v[112:113], v[112:113], 0, v[2:3]
	v_cvt_f32_ubyte0_e32 v1, v198
	global_store_dwordx4 v[112:113], v[108:111], off
	s_nop 1
	v_max_f32_e32 v108, 0.5, v1
	v_cvt_f32_ubyte1_e32 v1, v198
	v_max_f32_e32 v109, 0.5, v1
	v_cvt_f32_ubyte2_e32 v1, v198
	v_max_f32_e32 v110, 0.5, v1
	v_cvt_f32_ubyte3_e32 v1, v198
	v_max_f32_e32 v111, 0.5, v1
	v_cvt_f32_ubyte0_e32 v1, v199
	v_max_f32_e32 v114, 0.5, v1
; __device__ __forceinline__ u32x4 pack8(f32x4 a, f32x4 b) { u32x4 w; w.x = cvt_pk_bf16(a[0], a[1]); w.y = cvt_pk_bf16(a[2], a[3]); w.z = cvt_pk_bf16(b[0], b[1]); w.w = cvt_pk_bf16(b[2], b[3]); return w; }
; __device__ __forceinline__ f32x4 un_unorm8(unsigned w) { return (f32x4){fmaxf((float)(w & 255u), 0.5f), fmaxf((float)((w >> 8) & 255u), 0.5f), fmaxf((float)((w >> 16) & 255u), 0.5f), fmaxf((float)(w >> 24), 0.5f)}; }
;     __device__ __forceinline__ void operator()(f32x4 (&acc)[2][2][4][2], const Unit& u, int wr, int wc, int fr, int fq) const {
;     ...
;             for (int m = 0; m < 4; ++m)
; #pragma unroll
;                 for (int bj = 0; bj < 2; ++bj) { const int row = u.pm * 256 + ai * 128 + wr * 64 + m * 16 + fr, col = u.pn * 256 + bj * 128 + wc * 32 + 8 * fq;
;                     gg[m][bj] = *(const u32x2*)((const unsigned char*)P + (size_t)row * ROWB + GATE_B0 + 2 * DM + col); }
;             asm volatile("" ::: "memory");
;     ...
;             for (int m = 0; m < 4; ++m)
; #pragma unroll
;                 for (int bj = 0; bj < 2; ++bj) { const int row = u.pm * 256 + ai * 128 + wr * 64 + m * 16 + fr, col = u.pn * 256 + bj * 128 + wc * 32 + 8 * fq;
;                     const f32x4 g0 = un_unorm8(gg[m][bj].x) * (1.0f / 255.0f), g1 = un_unorm8(gg[m][bj].y) * (1.0f / 255.0f);
;                     *(u32x4*)(MG + (size_t)row * DM + col) = pack8(acc[ai][bj][m][0] * g0, acc[ai][bj][m][1] * g1); }
	v_cvt_f32_ubyte1_e32 v1, v199
	v_max_f32_e32 v115, 0.5, v1
	v_cvt_f32_ubyte2_e32 v1, v199
	v_max_f32_e32 v116, 0.5, v1
	v_cvt_f32_ubyte3_e32 v1, v199
	v_max_f32_e32 v117, 0.5, v1
	v_pk_mul_f32 v[108:109], v[108:109], s[86:87] op_sel_hi:[1,0]
	v_pk_mul_f32 v[110:111], v[110:111], s[86:87] op_sel_hi:[1,0]
	v_pk_mul_f32 v[114:115], v[114:115], s[86:87] op_sel_hi:[1,0]
	v_pk_mul_f32 v[116:117], v[116:117], s[86:87] op_sel_hi:[1,0]
	v_pk_mul_f32 v[106:107], v[106:107], v[110:111]
	v_pk_mul_f32 v[104:105], v[104:105], v[108:109]
	v_pk_mul_f32 v[108:109], v[102:103], v[116:117]
	v_pk_mul_f32 v[102:103], v[100:101], v[114:115]
	v_cvt_pk_bf16_f32 v100, v104, v105
	v_cvt_pk_bf16_f32 v101, v106, v107
	v_cvt_pk_bf16_f32 v102, v102, v103
	v_cvt_pk_bf16_f32 v103, v108, v109
	v_cvt_f32_ubyte0_e32 v1, v200
	global_store_dwordx4 v[112:113], v[100:103], off offset:256
	s_nop 1
	v_max_f32_e32 v102, 0.5, v1
	v_cvt_f32_ubyte1_e32 v1, v200
	v_max_f32_e32 v103, 0.5, v1
	v_cvt_f32_ubyte2_e32 v1, v200
	v_max_f32_e32 v104, 0.5, v1
	v_cvt_f32_ubyte3_e32 v1, v200
	v_max_f32_e32 v105, 0.5, v1
	v_cvt_f32_ubyte0_e32 v1, v201
	v_max_f32_e32 v106, 0.5, v1
	v_cvt_f32_ubyte1_e32 v1, v201
	v_max_f32_e32 v107, 0.5, v1
	v_cvt_f32_ubyte2_e32 v1, v201
	v_max_f32_e32 v108, 0.5, v1
	v_cvt_f32_ubyte3_e32 v1, v201
	v_pk_mul_f32 v[102:103], v[102:103], s[86:87] op_sel_hi:[1,0]
	v_max_f32_e32 v109, 0.5, v1
	v_lshlrev_b64 v[100:101], 12, v[170:171]
	v_pk_mul_f32 v[104:105], v[104:105], s[86:87] op_sel_hi:[1,0]
	v_pk_mul_f32 v[106:107], v[106:107], s[86:87] op_sel_hi:[1,0]
	v_pk_mul_f32 v[108:109], v[108:109], s[86:87] op_sel_hi:[1,0]
	v_pk_mul_f32 v[96:97], v[96:97], v[102:103]
	v_pk_mul_f32 v[98:99], v[98:99], v[104:105]
	v_pk_mul_f32 v[102:103], v[94:95], v[108:109]
	v_pk_mul_f32 v[94:95], v[92:93], v[106:107]
	v_cvt_pk_bf16_f32 v92, v96, v97
	v_lshl_add_u64 v[96:97], s[72:73], 0, v[100:101]
	v_cvt_pk_bf16_f32 v93, v98, v99
	v_cvt_pk_bf16_f32 v94, v94, v95
	v_cvt_pk_bf16_f32 v95, v102, v103
	v_lshl_add_u64 v[96:97], v[96:97], 0, v[2:3]
	v_cvt_f32_ubyte0_e32 v1, v202
	global_store_dwordx4 v[96:97], v[92:95], off
	s_nop 1
	v_max_f32_e32 v92, 0.5, v1
	v_cvt_f32_ubyte1_e32 v1, v202
	v_max_f32_e32 v93, 0.5, v1
	v_cvt_f32_ubyte2_e32 v1, v202
	v_max_f32_e32 v94, 0.5, v1
	v_cvt_f32_ubyte3_e32 v1, v202
	v_max_f32_e32 v95, 0.5, v1
	v_cvt_f32_ubyte0_e32 v1, v203
	v_max_f32_e32 v98, 0.5, v1
	v_cvt_f32_ubyte1_e32 v1, v203
	v_max_f32_e32 v99, 0.5, v1
	v_cvt_f32_ubyte2_e32 v1, v203
	v_max_f32_e32 v100, 0.5, v1
	v_cvt_f32_ubyte3_e32 v1, v203
	v_max_f32_e32 v101, 0.5, v1
	v_pk_mul_f32 v[92:93], v[92:93], s[86:87] op_sel_hi:[1,0]
	v_pk_mul_f32 v[94:95], v[94:95], s[86:87] op_sel_hi:[1,0]
	v_pk_mul_f32 v[98:99], v[98:99], s[86:87] op_sel_hi:[1,0]
	v_pk_mul_f32 v[100:101], v[100:101], s[86:87] op_sel_hi:[1,0]
	v_pk_mul_f32 v[90:91], v[90:91], v[94:95]
	v_pk_mul_f32 v[88:89], v[88:89], v[92:93]
	v_pk_mul_f32 v[92:93], v[86:87], v[100:101]
	v_pk_mul_f32 v[86:87], v[84:85], v[98:99]
	v_cvt_pk_bf16_f32 v84, v88, v89
	v_cvt_pk_bf16_f32 v85, v90, v91
	v_cvt_pk_bf16_f32 v86, v86, v87
	v_cvt_pk_bf16_f32 v87, v92, v93
	v_cvt_f32_ubyte0_e32 v1, v204
	global_store_dwordx4 v[96:97], v[84:87], off offset:256
	s_nop 1
	v_max_f32_e32 v86, 0.5, v1
	v_cvt_f32_ubyte1_e32 v1, v204
	v_max_f32_e32 v87, 0.5, v1
	v_cvt_f32_ubyte2_e32 v1, v204
	v_max_f32_e32 v88, 0.5, v1
	v_cvt_f32_ubyte3_e32 v1, v204
	v_max_f32_e32 v89, 0.5, v1
	v_cvt_f32_ubyte0_e32 v1, v205
	v_max_f32_e32 v90, 0.5, v1
	v_cvt_f32_ubyte1_e32 v1, v205
	v_max_f32_e32 v91, 0.5, v1
	v_cvt_f32_ubyte2_e32 v1, v205
	v_max_f32_e32 v92, 0.5, v1
	v_cvt_f32_ubyte3_e32 v1, v205
	v_pk_mul_f32 v[86:87], v[86:87], s[86:87] op_sel_hi:[1,0]
	v_max_f32_e32 v93, 0.5, v1
	v_lshlrev_b64 v[84:85], 12, v[156:157]
	v_pk_mul_f32 v[88:89], v[88:89], s[86:87] op_sel_hi:[1,0]
	v_pk_mul_f32 v[90:91], v[90:91], s[86:87] op_sel_hi:[1,0]
	v_pk_mul_f32 v[92:93], v[92:93], s[86:87] op_sel_hi:[1,0]
	v_pk_mul_f32 v[80:81], v[80:81], v[86:87]
	v_pk_mul_f32 v[82:83], v[82:83], v[88:89]
	v_pk_mul_f32 v[86:87], v[78:79], v[92:93]
	v_pk_mul_f32 v[78:79], v[76:77], v[90:91]
	v_cvt_pk_bf16_f32 v76, v80, v81
	v_lshl_add_u64 v[80:81], s[72:73], 0, v[84:85]
	v_cvt_pk_bf16_f32 v77, v82, v83
	v_cvt_pk_bf16_f32 v78, v78, v79
	v_cvt_pk_bf16_f32 v79, v86, v87
	v_lshl_add_u64 v[80:81], v[80:81], 0, v[2:3]
	v_cvt_f32_ubyte0_e32 v1, v206
	global_store_dwordx4 v[80:81], v[76:79], off
	v_add_u32_e32 v88, 0xa0, v146
	v_ashrrev_i32_e32 v89, 31, v88
	v_max_f32_e32 v76, 0.5, v1
	v_cvt_f32_ubyte1_e32 v1, v206
	v_max_f32_e32 v77, 0.5, v1
	v_cvt_f32_ubyte2_e32 v1, v206
	v_max_f32_e32 v78, 0.5, v1
	v_cvt_f32_ubyte3_e32 v1, v206
	v_max_f32_e32 v79, 0.5, v1
	v_cvt_f32_ubyte0_e32 v1, v207
	v_max_f32_e32 v82, 0.5, v1
	v_cvt_f32_ubyte1_e32 v1, v207
	v_max_f32_e32 v83, 0.5, v1
	v_cvt_f32_ubyte2_e32 v1, v207
	v_max_f32_e32 v84, 0.5, v1
	v_cvt_f32_ubyte3_e32 v1, v207
	v_max_f32_e32 v85, 0.5, v1
	v_pk_mul_f32 v[76:77], v[76:77], s[86:87] op_sel_hi:[1,0]
	v_pk_mul_f32 v[78:79], v[78:79], s[86:87] op_sel_hi:[1,0]
	v_pk_mul_f32 v[82:83], v[82:83], s[86:87] op_sel_hi:[1,0]
	v_pk_mul_f32 v[84:85], v[84:85], s[86:87] op_sel_hi:[1,0]
	v_pk_mul_f32 v[74:75], v[74:75], v[78:79]
	v_pk_mul_f32 v[72:73], v[72:73], v[76:77]
	v_pk_mul_f32 v[76:77], v[70:71], v[84:85]
	v_pk_mul_f32 v[70:71], v[68:69], v[82:83]
	v_cvt_pk_bf16_f32 v68, v72, v73
	v_cvt_pk_bf16_f32 v69, v74, v75
	v_cvt_pk_bf16_f32 v70, v70, v71
	v_cvt_pk_bf16_f32 v71, v76, v77
	v_add_u32_e32 v76, 0x80, v146
	global_store_dwordx4 v[80:81], v[68:71], off offset:256
	v_add_u32_e32 v82, 0x90, v146
	v_add_u32_e32 v72, 0xb0, v146
	v_mad_i64_i32 v[68:69], s[4:5], v76, s33, v[150:151]
	v_lshl_add_u64 v[68:69], v[68:69], 0, s[84:85]
	v_lshl_add_u64 v[70:71], v[68:69], 0, v[246:247]
	global_load_dwordx2 v[78:79], v[70:71], off
	v_lshl_add_u64 v[68:69], v[68:69], 0, v[148:149]
	global_load_dwordx2 v[80:81], v[68:69], off
	v_mad_i64_i32 v[68:69], s[4:5], v82, s33, v[150:151]
	v_lshl_add_u64 v[68:69], v[68:69], 0, s[84:85]
	v_lshl_add_u64 v[70:71], v[68:69], 0, v[246:247]
	global_load_dwordx2 v[84:85], v[70:71], off
	v_lshl_add_u64 v[68:69], v[68:69], 0, v[148:149]
	global_load_dwordx2 v[86:87], v[68:69], off
	v_mad_i64_i32 v[68:69], s[4:5], v88, s33, v[150:151]
	v_lshl_add_u64 v[68:69], v[68:69], 0, s[84:85]
	v_lshl_add_u64 v[70:71], v[68:69], 0, v[246:247]
	global_load_dwordx2 v[90:91], v[70:71], off
	v_lshl_add_u64 v[68:69], v[68:69], 0, v[148:149]
	global_load_dwordx2 v[74:75], v[68:69], off
	v_mad_i64_i32 v[68:69], s[4:5], v72, s33, v[150:151]
	v_lshl_add_u64 v[68:69], v[68:69], 0, s[84:85]
	v_lshl_add_u64 v[70:71], v[68:69], 0, v[246:247]
	global_load_dwordx2 v[70:71], v[70:71], off
	v_lshl_add_u64 v[68:69], v[68:69], 0, v[148:149]
	global_load_dwordx2 v[68:69], v[68:69], off
	v_ashrrev_i32_e32 v77, 31, v76
	v_lshlrev_b64 v[76:77], 12, v[76:77]
	v_ashrrev_i32_e32 v83, 31, v82
	v_ashrrev_i32_e32 v73, 31, v72
	s_mov_b64 s[4:5], -1
	s_waitcnt vmcnt(7)
; __device__ __forceinline__ u32x4 pack8(f32x4 a, f32x4 b) { u32x4 w; w.x = cvt_pk_bf16(a[0], a[1]); w.y = cvt_pk_bf16(a[2], a[3]); w.z = cvt_pk_bf16(b[0], b[1]); w.w = cvt_pk_bf16(b[2], b[3]); return w; }
; __device__ __forceinline__ f32x4 un_unorm8(unsigned w) { return (f32x4){fmaxf((float)(w & 255u), 0.5f), fmaxf((float)((w >> 8) & 255u), 0.5f), fmaxf((float)((w >> 16) & 255u), 0.5f), fmaxf((float)(w >> 24), 0.5f)}; }
;     __device__ __forceinline__ void operator()(f32x4 (&acc)[2][2][4][2], const Unit& u, int wr, int wc, int fr, int fq) const {
;     ...
;             for (int m = 0; m < 4; ++m)
; #pragma unroll
;                 for (int bj = 0; bj < 2; ++bj) { const int row = u.pm * 256 + ai * 128 + wr * 64 + m * 16 + fr, col = u.pn * 256 + bj * 128 + wc * 32 + 8 * fq;
;                     const f32x4 g0 = un_unorm8(gg[m][bj].x) * (1.0f / 255.0f), g1 = un_unorm8(gg[m][bj].y) * (1.0f / 255.0f);
;                     *(u32x4*)(MG + (size_t)row * DM + col) = pack8(acc[ai][bj][m][0] * g0, acc[ai][bj][m][1] * g1); }
	v_cvt_f32_ubyte0_e32 v1, v78
	v_max_f32_e32 v92, 0.5, v1
	v_cvt_f32_ubyte1_e32 v1, v78
	v_max_f32_e32 v93, 0.5, v1
	v_cvt_f32_ubyte2_e32 v1, v78
	v_max_f32_e32 v94, 0.5, v1
	v_cvt_f32_ubyte3_e32 v1, v78
	v_max_f32_e32 v95, 0.5, v1
	v_cvt_f32_ubyte0_e32 v1, v79
	v_max_f32_e32 v96, 0.5, v1
	v_cvt_f32_ubyte1_e32 v1, v79
	v_max_f32_e32 v97, 0.5, v1
	v_cvt_f32_ubyte2_e32 v1, v79
	v_max_f32_e32 v78, 0.5, v1
	v_cvt_f32_ubyte3_e32 v1, v79
	v_pk_mul_f32 v[92:93], v[92:93], s[86:87] op_sel_hi:[1,0]
	v_max_f32_e32 v79, 0.5, v1
	v_pk_mul_f32 v[94:95], v[94:95], s[86:87] op_sel_hi:[1,0]
	v_pk_mul_f32 v[96:97], v[96:97], s[86:87] op_sel_hi:[1,0]
	v_pk_mul_f32 v[78:79], v[78:79], s[86:87] op_sel_hi:[1,0]
	v_pk_mul_f32 v[64:65], v[64:65], v[92:93]
	v_pk_mul_f32 v[66:67], v[66:67], v[94:95]
	v_pk_mul_f32 v[78:79], v[62:63], v[78:79]
	v_pk_mul_f32 v[62:63], v[60:61], v[96:97]
	v_cvt_pk_bf16_f32 v60, v64, v65
	v_lshl_add_u64 v[64:65], s[72:73], 0, v[76:77]
	v_cvt_pk_bf16_f32 v61, v66, v67
	v_cvt_pk_bf16_f32 v62, v62, v63
	v_cvt_pk_bf16_f32 v63, v78, v79
	v_lshl_add_u64 v[64:65], v[64:65], 0, v[2:3]
	s_waitcnt vmcnt(6)
	v_cvt_f32_ubyte0_e32 v1, v80
	global_store_dwordx4 v[64:65], v[60:63], off
	s_nop 1
	v_max_f32_e32 v60, 0.5, v1
	v_cvt_f32_ubyte1_e32 v1, v80
	v_max_f32_e32 v61, 0.5, v1
	v_cvt_f32_ubyte2_e32 v1, v80
	v_max_f32_e32 v62, 0.5, v1
	v_cvt_f32_ubyte3_e32 v1, v80
	v_max_f32_e32 v63, 0.5, v1
	v_cvt_f32_ubyte0_e32 v1, v81
	v_max_f32_e32 v66, 0.5, v1
	v_cvt_f32_ubyte1_e32 v1, v81
	v_max_f32_e32 v67, 0.5, v1
	v_cvt_f32_ubyte2_e32 v1, v81
	v_max_f32_e32 v76, 0.5, v1
	v_cvt_f32_ubyte3_e32 v1, v81
	v_max_f32_e32 v77, 0.5, v1
	v_pk_mul_f32 v[60:61], v[60:61], s[86:87] op_sel_hi:[1,0]
	v_pk_mul_f32 v[62:63], v[62:63], s[86:87] op_sel_hi:[1,0]
	v_pk_mul_f32 v[66:67], v[66:67], s[86:87] op_sel_hi:[1,0]
	v_pk_mul_f32 v[76:77], v[76:77], s[86:87] op_sel_hi:[1,0]
	v_pk_mul_f32 v[58:59], v[58:59], v[62:63]
	v_pk_mul_f32 v[56:57], v[56:57], v[60:61]
	v_pk_mul_f32 v[60:61], v[54:55], v[76:77]
	v_pk_mul_f32 v[54:55], v[52:53], v[66:67]
	v_cvt_pk_bf16_f32 v52, v56, v57
	v_cvt_pk_bf16_f32 v53, v58, v59
	v_cvt_pk_bf16_f32 v54, v54, v55
	v_cvt_pk_bf16_f32 v55, v60, v61
	s_waitcnt vmcnt(6)
	v_cvt_f32_ubyte0_e32 v1, v84
	global_store_dwordx4 v[64:65], v[52:55], off offset:256
	s_nop 1
	v_max_f32_e32 v54, 0.5, v1
	v_cvt_f32_ubyte1_e32 v1, v84
	v_max_f32_e32 v55, 0.5, v1
	v_cvt_f32_ubyte2_e32 v1, v84
	v_max_f32_e32 v56, 0.5, v1
	v_cvt_f32_ubyte3_e32 v1, v84
	v_max_f32_e32 v57, 0.5, v1
	v_cvt_f32_ubyte0_e32 v1, v85
	v_max_f32_e32 v58, 0.5, v1
	v_cvt_f32_ubyte1_e32 v1, v85
	v_max_f32_e32 v59, 0.5, v1
	v_cvt_f32_ubyte2_e32 v1, v85
	v_max_f32_e32 v60, 0.5, v1
	v_cvt_f32_ubyte3_e32 v1, v85
	v_pk_mul_f32 v[54:55], v[54:55], s[86:87] op_sel_hi:[1,0]
	v_max_f32_e32 v61, 0.5, v1
	v_lshlrev_b64 v[52:53], 12, v[82:83]
	v_pk_mul_f32 v[56:57], v[56:57], s[86:87] op_sel_hi:[1,0]
	v_pk_mul_f32 v[58:59], v[58:59], s[86:87] op_sel_hi:[1,0]
	v_pk_mul_f32 v[60:61], v[60:61], s[86:87] op_sel_hi:[1,0]
	v_pk_mul_f32 v[48:49], v[48:49], v[54:55]
	v_pk_mul_f32 v[50:51], v[50:51], v[56:57]
	v_pk_mul_f32 v[54:55], v[46:47], v[60:61]
	v_pk_mul_f32 v[46:47], v[44:45], v[58:59]
	v_cvt_pk_bf16_f32 v44, v48, v49
	v_lshl_add_u64 v[48:49], s[72:73], 0, v[52:53]
	v_cvt_pk_bf16_f32 v45, v50, v51
	v_cvt_pk_bf16_f32 v46, v46, v47
	v_cvt_pk_bf16_f32 v47, v54, v55
	v_lshl_add_u64 v[48:49], v[48:49], 0, v[2:3]
	s_waitcnt vmcnt(6)
	v_cvt_f32_ubyte0_e32 v1, v86
	global_store_dwordx4 v[48:49], v[44:47], off
	s_nop 1
	v_max_f32_e32 v44, 0.5, v1
	v_cvt_f32_ubyte1_e32 v1, v86
	v_max_f32_e32 v45, 0.5, v1
	v_cvt_f32_ubyte2_e32 v1, v86
	v_max_f32_e32 v46, 0.5, v1
	v_cvt_f32_ubyte3_e32 v1, v86
	v_max_f32_e32 v47, 0.5, v1
	v_cvt_f32_ubyte0_e32 v1, v87
	v_max_f32_e32 v50, 0.5, v1
	v_cvt_f32_ubyte1_e32 v1, v87
	v_max_f32_e32 v51, 0.5, v1
	v_cvt_f32_ubyte2_e32 v1, v87
	v_max_f32_e32 v52, 0.5, v1
	v_cvt_f32_ubyte3_e32 v1, v87
	v_max_f32_e32 v53, 0.5, v1
	v_pk_mul_f32 v[44:45], v[44:45], s[86:87] op_sel_hi:[1,0]
	v_pk_mul_f32 v[46:47], v[46:47], s[86:87] op_sel_hi:[1,0]
	v_pk_mul_f32 v[50:51], v[50:51], s[86:87] op_sel_hi:[1,0]
	v_pk_mul_f32 v[52:53], v[52:53], s[86:87] op_sel_hi:[1,0]
	v_pk_mul_f32 v[42:43], v[42:43], v[46:47]
	v_pk_mul_f32 v[40:41], v[40:41], v[44:45]
	v_pk_mul_f32 v[44:45], v[38:39], v[52:53]
	v_pk_mul_f32 v[38:39], v[36:37], v[50:51]
	v_cvt_pk_bf16_f32 v36, v40, v41
	v_cvt_pk_bf16_f32 v37, v42, v43
	v_cvt_pk_bf16_f32 v38, v38, v39
	v_cvt_pk_bf16_f32 v39, v44, v45
	s_waitcnt vmcnt(6)
; __device__ __forceinline__ u32x4 pack8(f32x4 a, f32x4 b) { u32x4 w; w.x = cvt_pk_bf16(a[0], a[1]); w.y = cvt_pk_bf16(a[2], a[3]); w.z = cvt_pk_bf16(b[0], b[1]); w.w = cvt_pk_bf16(b[2], b[3]); return w; }
; __device__ __forceinline__ f32x4 un_unorm8(unsigned w) { return (f32x4){fmaxf((float)(w & 255u), 0.5f), fmaxf((float)((w >> 8) & 255u), 0.5f), fmaxf((float)((w >> 16) & 255u), 0.5f), fmaxf((float)(w >> 24), 0.5f)}; }
; #define PG8_BAR __builtin_amdgcn_s_barrier()
; template <class Epi, class Order = StaticOrder, bool HALFN = false>
; __device__ __forceinline__ void gemm_phase(LAS unsigned char* lds, const Gemm g, const Epi& E) {
;     ...
;         cur = nxt; cA = nA; cB = nB; ++ui;
;         if (wr == 1) PG8_BAR;
;     __device__ __forceinline__ void operator()(f32x4 (&acc)[2][2][4][2], const Unit& u, int wr, int wc, int fr, int fq) const {
;     ...
;             for (int m = 0; m < 4; ++m)
; #pragma unroll
;                 for (int bj = 0; bj < 2; ++bj) { const int row = u.pm * 256 + ai * 128 + wr * 64 + m * 16 + fr, col = u.pn * 256 + bj * 128 + wc * 32 + 8 * fq;
;                     const f32x4 g0 = un_unorm8(gg[m][bj].x) * (1.0f / 255.0f), g1 = un_unorm8(gg[m][bj].y) * (1.0f / 255.0f);
;                     *(u32x4*)(MG + (size_t)row * DM + col) = pack8(acc[ai][bj][m][0] * g0, acc[ai][bj][m][1] * g1); }
;             asm volatile("" ::: "memory");
;         }
	v_cvt_f32_ubyte0_e32 v1, v90
	global_store_dwordx4 v[48:49], v[36:39], off offset:256
	s_nop 1
	v_max_f32_e32 v38, 0.5, v1
	v_cvt_f32_ubyte1_e32 v1, v90
	v_max_f32_e32 v39, 0.5, v1
	v_cvt_f32_ubyte2_e32 v1, v90
	v_max_f32_e32 v40, 0.5, v1
	v_cvt_f32_ubyte3_e32 v1, v90
	v_max_f32_e32 v41, 0.5, v1
	v_cvt_f32_ubyte0_e32 v1, v91
	v_max_f32_e32 v42, 0.5, v1
	v_cvt_f32_ubyte1_e32 v1, v91
	v_max_f32_e32 v43, 0.5, v1
	v_cvt_f32_ubyte2_e32 v1, v91
	v_max_f32_e32 v44, 0.5, v1
	v_cvt_f32_ubyte3_e32 v1, v91
	v_pk_mul_f32 v[38:39], v[38:39], s[86:87] op_sel_hi:[1,0]
	v_max_f32_e32 v45, 0.5, v1
	v_lshlrev_b64 v[36:37], 12, v[88:89]
	v_pk_mul_f32 v[40:41], v[40:41], s[86:87] op_sel_hi:[1,0]
	v_pk_mul_f32 v[42:43], v[42:43], s[86:87] op_sel_hi:[1,0]
	v_pk_mul_f32 v[44:45], v[44:45], s[86:87] op_sel_hi:[1,0]
	v_pk_mul_f32 v[32:33], v[32:33], v[38:39]
	v_pk_mul_f32 v[34:35], v[34:35], v[40:41]
	v_pk_mul_f32 v[38:39], v[30:31], v[44:45]
	v_pk_mul_f32 v[30:31], v[28:29], v[42:43]
	v_cvt_pk_bf16_f32 v28, v32, v33
	v_lshl_add_u64 v[32:33], s[72:73], 0, v[36:37]
	v_cvt_pk_bf16_f32 v29, v34, v35
	v_cvt_pk_bf16_f32 v30, v30, v31
	v_cvt_pk_bf16_f32 v31, v38, v39
	v_lshl_add_u64 v[32:33], v[32:33], 0, v[2:3]
	s_waitcnt vmcnt(6)
	v_cvt_f32_ubyte0_e32 v1, v74
	global_store_dwordx4 v[32:33], v[28:31], off
	s_nop 1
	v_max_f32_e32 v28, 0.5, v1
	v_cvt_f32_ubyte1_e32 v1, v74
	v_max_f32_e32 v29, 0.5, v1
	v_cvt_f32_ubyte2_e32 v1, v74
	v_max_f32_e32 v30, 0.5, v1
	v_cvt_f32_ubyte3_e32 v1, v74
	v_max_f32_e32 v31, 0.5, v1
	v_cvt_f32_ubyte0_e32 v1, v75
	v_max_f32_e32 v34, 0.5, v1
	v_cvt_f32_ubyte1_e32 v1, v75
	v_max_f32_e32 v35, 0.5, v1
	v_cvt_f32_ubyte2_e32 v1, v75
	v_max_f32_e32 v36, 0.5, v1
	v_cvt_f32_ubyte3_e32 v1, v75
	v_max_f32_e32 v37, 0.5, v1
	v_pk_mul_f32 v[28:29], v[28:29], s[86:87] op_sel_hi:[1,0]
	v_pk_mul_f32 v[30:31], v[30:31], s[86:87] op_sel_hi:[1,0]
	v_pk_mul_f32 v[34:35], v[34:35], s[86:87] op_sel_hi:[1,0]
	v_pk_mul_f32 v[36:37], v[36:37], s[86:87] op_sel_hi:[1,0]
	v_pk_mul_f32 v[26:27], v[26:27], v[30:31]
	v_pk_mul_f32 v[24:25], v[24:25], v[28:29]
	v_pk_mul_f32 v[28:29], v[22:23], v[36:37]
	v_pk_mul_f32 v[22:23], v[20:21], v[34:35]
	v_cvt_pk_bf16_f32 v20, v24, v25
	v_cvt_pk_bf16_f32 v21, v26, v27
	v_cvt_pk_bf16_f32 v22, v22, v23
	v_cvt_pk_bf16_f32 v23, v28, v29
	s_waitcnt vmcnt(6)
	v_cvt_f32_ubyte0_e32 v1, v70
	global_store_dwordx4 v[32:33], v[20:23], off offset:256
	s_nop 1
	v_max_f32_e32 v22, 0.5, v1
	v_cvt_f32_ubyte1_e32 v1, v70
	v_max_f32_e32 v23, 0.5, v1
	v_cvt_f32_ubyte2_e32 v1, v70
	v_max_f32_e32 v24, 0.5, v1
	v_cvt_f32_ubyte3_e32 v1, v70
	v_max_f32_e32 v25, 0.5, v1
	v_cvt_f32_ubyte0_e32 v1, v71
	v_max_f32_e32 v26, 0.5, v1
	v_cvt_f32_ubyte1_e32 v1, v71
	v_max_f32_e32 v27, 0.5, v1
	v_cvt_f32_ubyte2_e32 v1, v71
	v_max_f32_e32 v28, 0.5, v1
	v_cvt_f32_ubyte3_e32 v1, v71
	v_pk_mul_f32 v[22:23], v[22:23], s[86:87] op_sel_hi:[1,0]
	v_max_f32_e32 v29, 0.5, v1
	v_lshlrev_b64 v[20:21], 12, v[72:73]
	v_pk_mul_f32 v[26:27], v[26:27], s[86:87] op_sel_hi:[1,0]
	v_pk_mul_f32 v[28:29], v[28:29], s[86:87] op_sel_hi:[1,0]
	v_pk_mul_f32 v[16:17], v[16:17], v[22:23]
	v_pk_mul_f32 v[24:25], v[24:25], s[86:87] op_sel_hi:[1,0]
	v_pk_mul_f32 v[22:23], v[14:15], v[28:29]
	v_pk_mul_f32 v[14:15], v[12:13], v[26:27]
	v_cvt_pk_bf16_f32 v12, v16, v17
	v_lshl_add_u64 v[16:17], s[72:73], 0, v[20:21]
	s_waitcnt vmcnt(6)
	v_cvt_f32_ubyte0_e32 v1, v68
	v_pk_mul_f32 v[18:19], v[18:19], v[24:25]
	v_lshl_add_u64 v[16:17], v[16:17], 0, v[2:3]
	v_max_f32_e32 v2, 0.5, v1
	v_cvt_f32_ubyte1_e32 v1, v68
	v_cvt_pk_bf16_f32 v13, v18, v19
	v_cvt_pk_bf16_f32 v14, v14, v15
	v_cvt_pk_bf16_f32 v15, v22, v23
	v_max_f32_e32 v3, 0.5, v1
	v_cvt_f32_ubyte2_e32 v1, v68
	global_store_dwordx4 v[16:17], v[12:15], off
	v_pk_mul_f32 v[2:3], v[2:3], s[86:87] op_sel_hi:[1,0]
	s_nop 0
	v_max_f32_e32 v12, 0.5, v1
	v_cvt_f32_ubyte3_e32 v1, v68
	v_max_f32_e32 v13, 0.5, v1
	v_cvt_f32_ubyte0_e32 v1, v69
	v_max_f32_e32 v14, 0.5, v1
	v_cvt_f32_ubyte1_e32 v1, v69
	v_max_f32_e32 v15, 0.5, v1
	v_cvt_f32_ubyte2_e32 v1, v69
	v_max_f32_e32 v18, 0.5, v1
	v_cvt_f32_ubyte3_e32 v1, v69
	v_max_f32_e32 v19, 0.5, v1
	v_pk_mul_f32 v[12:13], v[12:13], s[86:87] op_sel_hi:[1,0]
	v_pk_mul_f32 v[14:15], v[14:15], s[86:87] op_sel_hi:[1,0]
	v_pk_mul_f32 v[18:19], v[18:19], s[86:87] op_sel_hi:[1,0]
	v_pk_mul_f32 v[10:11], v[10:11], v[12:13]
	v_pk_mul_f32 v[2:3], v[8:9], v[2:3]
	v_pk_mul_f32 v[6:7], v[6:7], v[18:19]
	v_pk_mul_f32 v[4:5], v[4:5], v[14:15]
	v_cvt_pk_bf16_f32 v2, v2, v3
	v_cvt_pk_bf16_f32 v3, v10, v11
	v_cvt_pk_bf16_f32 v4, v4, v5
	v_cvt_pk_bf16_f32 v5, v6, v7
	global_store_dwordx4 v[16:17], v[2:5], off offset:256
	s_cbranch_vccnz .LBB0_597
	s_andn2_b64 vcc, exec, s[44:45]
	s_cbranch_vccnz .LBB0_596
	s_barrier
	s_branch .LBB0_596

; #define SEAML(k) do { if (IN(k) && IN((k) + 1)) xcd_barrier(xb, lx >= 0); } while (0)
; __device__ __forceinline__ void xcd_barrier(const XcdBarrier& b, bool local = false) {
;     asm volatile("s_waitcnt vmcnt(0)" ::: "memory");
;     __syncthreads();
;     if (threadIdx.x == 0) {
;         unsigned* bar = b.bar;
;         __builtin_amdgcn_s_waitcnt(0);
;         unsigned nloc = b.st[0], nx = b.st[1];
;         if (nloc == 0u) { xcd_barrier_complete(bar, b.x, nloc, nx); b.st[0] = nloc; b.st[1] = nx; }
; __global__ void __launch_bounds__(512, 2) fwd_megakernel(Args a) {
;     ...
;         SEAML(pb + 3);
.LBB0_627:
	v_mov_b32_e32 v192, 0x4800
	v_mov_b32_e32 v193, 0x1800
	v_mov_b32_e32 v194, 0x3e000000
	v_mov_b32_e32 v195, 0x3eaaaaab
	v_mov_b32_e32 v196, 0x3e800000
	v_mov_b32_e32 v197, 0x3e4ccccd
	v_mov_b32_e32 v198, 0x3e2aaaab
	v_mov_b32_e32 v199, 0x3e124925
	v_mov_b32_e32 v200, 0x3d800000
	v_mov_b32_e32 v201, 0x3de38e39
	v_mov_b32_e32 v202, 0x3dcccccd
	v_mov_b32_e32 v203, 0x3dba2e8c
	v_mov_b32_e32 v204, 0x3daaaaab
	v_mov_b32_e32 v205, 0x3d9d89d9
	v_mov_b32_e32 v206, 0x3d924925
	v_mov_b32_e32 v207, 0x3d888889
	v_readlane_b32 s4, v250, 1
	s_add_i32 s15, s4, 5
	s_cmp_ge_i32 s15, s97
	s_cbranch_scc1 .LBB0_683
	s_waitcnt vmcnt(0)
	s_waitcnt vmcnt(0)
	s_barrier
	s_mov_b64 s[40:41], exec
	v_readlane_b32 s4, v252, 2
	v_readlane_b32 s5, v252, 3
	s_and_b64 s[4:5], s[40:41], s[4:5]
	s_mov_b64 exec, s[4:5]
	s_cbranch_execz .LBB0_682
	v_readlane_b32 s4, v251, 57
	s_waitcnt vmcnt(0) expcnt(0) lgkmcnt(0)
	s_nop 0
	v_mov_b32_e32 v1, s4
	ds_read_b32 v3, v1
	v_readlane_b32 s4, v251, 58
	s_waitcnt lgkmcnt(0)
	v_cmp_ne_u32_e32 vcc, 0, v3
	v_mov_b32_e32 v1, s4
	ds_read_b32 v2, v1
	s_cbranch_vccnz .LBB0_644
	s_mov_b32 s10, 1
	s_branch .LBB0_632

; __global__ void __launch_bounds__(512, 2) fwd_megakernel(Args a) {
	.amdhsa_kernel _Z14fwd_megakernel4Args
		.amdhsa_group_segment_fixed_size 0
		.amdhsa_private_segment_fixed_size 0
		.amdhsa_kernarg_size 408
		.amdhsa_user_sgpr_count 2
		.amdhsa_user_sgpr_dispatch_ptr 0
		.amdhsa_user_sgpr_queue_ptr 0
		.amdhsa_user_sgpr_kernarg_segment_ptr 1
		.amdhsa_user_sgpr_dispatch_id 0
		.amdhsa_user_sgpr_kernarg_preload_length 0
		.amdhsa_user_sgpr_kernarg_preload_offset 0
		.amdhsa_user_sgpr_private_segment_size 0
		.amdhsa_uses_dynamic_stack 0
		.amdhsa_enable_private_segment 0
		.amdhsa_system_sgpr_workgroup_id_x 1
		.amdhsa_system_sgpr_workgroup_id_y 0
		.amdhsa_system_sgpr_workgroup_id_z 0
		.amdhsa_system_sgpr_workgroup_info 0
		.amdhsa_system_vgpr_workitem_id 2
		.amdhsa_next_free_vgpr 256
		.amdhsa_next_free_sgpr 100
		.amdhsa_accum_offset 256
		.amdhsa_reserve_vcc 1
		.amdhsa_float_round_mode_32 0
		.amdhsa_float_round_mode_16_64 0
		.amdhsa_float_denorm_mode_32 3
		.amdhsa_float_denorm_mode_16_64 3
		.amdhsa_dx10_clamp 1
		.amdhsa_ieee_mode 1
		.amdhsa_fp16_overflow 0
		.amdhsa_tg_split 0
		.amdhsa_exception_fp_ieee_invalid_op 0
		.amdhsa_exception_fp_denorm_src 0
		.amdhsa_exception_fp_ieee_div_zero 0
		.amdhsa_exception_fp_ieee_overflow 0
		.amdhsa_exception_fp_ieee_underflow 0
		.amdhsa_exception_fp_ieee_inexact 0
		.amdhsa_exception_int_div_zero 0
	.end_amdhsa_kernel

; __global__ void __launch_bounds__(512, 2) fwd_megakernel(Args a) {
amdhsa.kernels:
  - .agpr_count:     0
    .args:
      - .offset:         0
        .size:           152
        .value_kind:     by_value
      - .offset:         152
        .size:           4
        .value_kind:     hidden_block_count_x
      - .offset:         156
        .size:           4
        .value_kind:     hidden_block_count_y
      - .offset:         160
        .size:           4
        .value_kind:     hidden_block_count_z
      - .offset:         164
        .size:           2
        .value_kind:     hidden_group_size_x
      - .offset:         166
        .size:           2
        .value_kind:     hidden_group_size_y
      - .offset:         168
        .size:           2
        .value_kind:     hidden_group_size_z
      - .offset:         170
        .size:           2
        .value_kind:     hidden_remainder_x
      - .offset:         172
        .size:           2
        .value_kind:     hidden_remainder_y
      - .offset:         174
        .size:           2
        .value_kind:     hidden_remainder_z
      - .offset:         192
        .size:           8
        .value_kind:     hidden_global_offset_x
      - .offset:         200
        .size:           8
        .value_kind:     hidden_global_offset_y
      - .offset:         208
        .size:           8
        .value_kind:     hidden_global_offset_z
      - .offset:         216
        .size:           2
        .value_kind:     hidden_grid_dims
      - .offset:         240
        .size:           8
        .value_kind:     hidden_multigrid_sync_arg
      - .offset:         272
        .size:           4
        .value_kind:     hidden_dynamic_lds_size
    .group_segment_fixed_size: 0
    .kernarg_segment_align: 8
    .kernarg_segment_size: 408
    .language:       OpenCL C
    .language_version:
      - 2
      - 0
    .max_flat_workgroup_size: 512
    .name:           _Z14fwd_megakernel4Args
    .private_segment_fixed_size: 0
    .sgpr_count:     106
    .sgpr_spill_count: 198
    .symbol:         _Z14fwd_megakernel4Args.kd
    .uniform_work_group_size: 1
    .uses_dynamic_stack: false
    .vgpr_count:     256
    .vgpr_spill_count: 0
    .wavefront_size: 64
